# exact per-path vmcnt waits in DSA indexer ring, DSA sparse-attention and band step loops
# speedup vs baseline: 1.0040x; 1.0040x over previous
; #define LAS __attribute__((address_space(3)))
; #define MFMA16(a, b, c) __builtin_amdgcn_mfma_f32_16x16x32_bf16((a), (b), (c), 0, 0, 0)
; __device__ __forceinline__ void dsa_unit(int b, int blk, const bf16_t* P, bf16_t* OB, LAS unsigned char* lds, int wave, int tid_in) {
;     ...
;         { const u32x4 ww = *(const u32x4*)(qrow + PC_WI); f32x4 wa, wb; unpack8(ww, wa, wb);
; #pragma unroll
;           for (int e = 0; e < 4; ++e) { w[e] = wa[e]; w[4 + e] = wb[e]; } }
;         const int ntile = nk >> 4;
;         const bf16_t* kp0 = P + (tok0 + qi) * NP_ + PC_KI + 8 * g4;
;         bf16x8 kf[6][2];
; #pragma unroll
;         for (int i = 0; i < 5; ++i) if (wave + 8 * i < ntile) { const bf16_t* kp = kp0 + (size_t)(16 * (wave + 8 * i)) * NP_; kf[i][0] = *(const bf16x8*)kp; kf[i][1] = *(const bf16x8*)(kp + 32); }
;         for (int kt = wave; kt < ntile; kt += 48) {
; #pragma unroll
;             for (int j = 0; j < 6; ++j) {
;                 const int kc = kt + 8 * j;
;                 if (kc < ntile) {
;                     if (kc + 40 < ntile) { const bf16_t* kp = kp0 + (size_t)(16 * (kc + 40)) * NP_; kf[(j + 5) % 6][0] = *(const bf16x8*)kp; kf[(j + 5) % 6][1] = *(const bf16x8*)(kp + 32); }
;                     f32x4 sc = (f32x4){0.f, 0.f, 0.f, 0.f};
; #pragma unroll
;                     for (int h = 0; h < 8; ++h) { f32x4 s = (f32x4){0.f, 0.f, 0.f, 0.f}; s = MFMA16(kf[j][0], bqi[h][0], s); s = MFMA16(kf[j][1], bqi[h][1], s);
; #pragma unroll
;                         for (int e = 0; e < 4; ++e) sc[e] = fmaf(w[h], fmaxf(s[e], 0.f), sc[e]); }
;                     u32x2 o2;
;                     { const _Float16 h0 = (_Float16)sc[0], h1 = (_Float16)sc[1], h2 = (_Float16)sc[2], h3 = (_Float16)sc[3];
;                       o2.x = (unsigned)__builtin_bit_cast(unsigned short, h0) | ((unsigned)__builtin_bit_cast(unsigned short, h1) << 16);
;                       o2.y = (unsigned)__builtin_bit_cast(unsigned short, h2) | ((unsigned)__builtin_bit_cast(unsigned short, h3) << 16); }
;                     *(LAS u32x2*)(lds + qi * C_SCW + (16 * kc + 4 * g4) * 2) = o2;
;                 }
;             }
.LBB0_592:
	v_bfe_u32 v135, v133, 4, 2
	v_lshlrev_b32_e32 v134, 3, v135
	s_and_b64 vcc, exec, s[4:5]
	s_cbranch_vccz .LBB0_617
	v_mul_hi_u32_u24_e32 v111, 0x1c00, v112
	v_mul_u32_u24_e32 v110, 0x1c00, v112
	v_readlane_b32 s0, v254, 63
	s_waitcnt vmcnt(0)
	v_lshlrev_b32_e32 v114, 16, v106
	v_and_b32_e32 v116, 0xffff0000, v106
	v_lshlrev_b32_e32 v118, 16, v107
	v_and_b32_e32 v120, 0xffff0000, v107
	v_lshl_add_u64 v[106:107], v[110:111], 0, v[0:1]
	v_readlane_b32 s1, v255, 0
	v_lshlrev_b32_e32 v122, 16, v108
	v_and_b32_e32 v124, 0xffff0000, v108
	v_lshlrev_b32_e32 v126, 16, v109
	v_and_b32_e32 v128, 0xffff0000, v109
	v_mul_u32_u24_e32 v108, 0x1010, v132
	v_lshl_add_u64 v[130:131], s[0:1], 0, v[106:107]
	v_readlane_b32 s0, v255, 2
	v_mov_b32_e32 v129, v128
	v_mov_b32_e32 v127, v126
	v_mov_b32_e32 v125, v124
	v_mov_b32_e32 v123, v122
	v_mov_b32_e32 v121, v120
	v_mov_b32_e32 v119, v118
	v_mov_b32_e32 v117, v116
	v_mov_b32_e32 v115, v114
	v_add3_u32 v0, v108, v134, s0
	v_readlane_b32 s2, v255, 5
	s_branch .LBB0_596
.LBB0_594:
	s_waitcnt vmcnt(0)
.Ls1body_594:
	s_nop 0
	v_mfma_f32_16x16x32_bf16 v[136:139], v[110:113], v[2:5], 0
	s_nop 0
	v_mfma_f32_16x16x32_bf16 v[136:139], v[106:109], v[6:9], v[136:139]
	v_mfma_f32_16x16x32_bf16 v[140:143], v[110:113], v[10:13], 0
	s_nop 6
	v_max_f32_e32 v136, v136, v136
	v_max_f32_e32 v137, v137, v137
	v_max_f32_e32 v138, v138, v138
	v_max_f32_e32 v136, 0, v136
	v_max_f32_e32 v144, 0, v137
	v_max_f32_e32 v137, 0, v138
	v_pk_fma_f32 v[146:147], v[114:115], v[136:137], 0 op_sel_hi:[1,1,0]
	v_max_f32_e32 v136, v139, v139
	v_max_f32_e32 v145, 0, v136
	v_mfma_f32_16x16x32_bf16 v[136:139], v[106:109], v[14:17], v[140:143]
	s_nop 2
	v_fma_f32 v142, v114, v144, 0
	v_fma_f32 v143, v115, v145, 0
	s_nop 2
	v_max_f32_e32 v136, v136, v136
	v_max_f32_e32 v148, 0, v136
	v_max_f32_e32 v136, v137, v137
	v_max_f32_e32 v140, 0, v136
	v_max_f32_e32 v136, v138, v138
	v_max_f32_e32 v149, 0, v136
	v_max_f32_e32 v141, v139, v139
	v_mfma_f32_16x16x32_bf16 v[136:139], v[110:113], v[18:21], 0
	v_max_f32_e32 v141, 0, v141
	v_pk_fma_f32 v[144:145], v[116:117], v[140:141], v[142:143]
	v_mfma_f32_16x16x32_bf16 v[136:139], v[106:109], v[22:25], v[136:139]
	v_mfma_f32_16x16x32_bf16 v[140:143], v[110:113], v[26:29], 0
	s_nop 6
	v_max_f32_e32 v136, v136, v136
	v_max_f32_e32 v150, 0, v136
	v_max_f32_e32 v136, v137, v137
	v_max_f32_e32 v152, 0, v136
	v_max_f32_e32 v136, v138, v138
	v_max_f32_e32 v151, 0, v136
	v_max_f32_e32 v136, v139, v139
	v_max_f32_e32 v153, 0, v136
	v_mfma_f32_16x16x32_bf16 v[136:139], v[106:109], v[30:33], v[140:143]
	v_mfma_f32_16x16x32_bf16 v[140:143], v[110:113], v[34:37], 0
	s_nop 6
	v_max_f32_e32 v136, v136, v136
	v_max_f32_e32 v154, 0, v136
	v_max_f32_e32 v136, v137, v137
	v_max_f32_e32 v156, 0, v136
	v_max_f32_e32 v136, v138, v138
	v_max_f32_e32 v155, 0, v136
	v_max_f32_e32 v136, v139, v139
	v_max_f32_e32 v157, 0, v136
	v_mfma_f32_16x16x32_bf16 v[136:139], v[106:109], v[38:41], v[140:143]
	v_mfma_f32_16x16x32_bf16 v[140:143], v[110:113], v[42:45], 0
	s_nop 6
	v_max_f32_e32 v136, v136, v136
	v_max_f32_e32 v158, 0, v136
	v_max_f32_e32 v136, v137, v137
	v_max_f32_e32 v160, 0, v136
	v_max_f32_e32 v136, v138, v138
	v_max_f32_e32 v159, 0, v136
	v_max_f32_e32 v136, v139, v139
	v_max_f32_e32 v161, 0, v136
	v_mfma_f32_16x16x32_bf16 v[136:139], v[106:109], v[46:49], v[140:143]
	v_mfma_f32_16x16x32_bf16 v[140:143], v[110:113], v[50:53], 0
	s_nop 6
	v_max_f32_e32 v136, v136, v136
	v_max_f32_e32 v162, 0, v136
	v_max_f32_e32 v136, v137, v137
	v_max_f32_e32 v164, 0, v136
	v_max_f32_e32 v136, v138, v138
	v_max_f32_e32 v163, 0, v136
	v_max_f32_e32 v136, v139, v139
	v_max_f32_e32 v165, 0, v136
	v_mfma_f32_16x16x32_bf16 v[136:139], v[106:109], v[54:57], v[140:143]
	v_mfma_f32_16x16x32_bf16 v[140:143], v[110:113], v[58:61], 0
	s_nop 6
	v_max_f32_e32 v136, v136, v136
	v_max_f32_e32 v166, 0, v136
	v_max_f32_e32 v136, v137, v137
	v_max_f32_e32 v168, 0, v136
	v_max_f32_e32 v136, v138, v138
	v_max_f32_e32 v167, 0, v136
	v_max_f32_e32 v136, v139, v139
	v_max_f32_e32 v169, 0, v136
	v_mfma_f32_16x16x32_bf16 v[136:139], v[106:109], v[62:65], v[140:143]
	s_nop 2
	v_fma_f32 v142, v118, v152, v144
	v_fma_f32 v143, v119, v153, v145
	v_pk_fma_f32 v[142:143], v[120:121], v[156:157], v[142:143]
	s_nop 1
	v_max_f32_e32 v137, v137, v137
	v_max_f32_e32 v140, 0, v137
	v_max_f32_e32 v137, v138, v138
	v_max_f32_e32 v138, v139, v139
	v_max_f32_e32 v141, 0, v138
	v_pk_fma_f32 v[138:139], v[116:117], v[148:149], v[146:147]
	v_pk_fma_f32 v[142:143], v[122:123], v[160:161], v[142:143]
	v_pk_fma_f32 v[138:139], v[118:119], v[150:151], v[138:139]
	v_max_f32_e32 v136, v136, v136
	v_pk_fma_f32 v[138:139], v[120:121], v[154:155], v[138:139]
	v_pk_fma_f32 v[142:143], v[124:125], v[164:165], v[142:143]
	v_pk_fma_f32 v[138:139], v[122:123], v[158:159], v[138:139]
	v_max_f32_e32 v136, 0, v136
	v_pk_fma_f32 v[138:139], v[124:125], v[162:163], v[138:139]
	v_max_f32_e32 v137, 0, v137
	v_pk_fma_f32 v[138:139], v[126:127], v[166:167], v[138:139]
	v_pk_fma_f32 v[142:143], v[126:127], v[168:169], v[142:143]
	v_pk_fma_f32 v[136:137], v[128:129], v[136:137], v[138:139]
	v_pk_fma_f32 v[138:139], v[128:129], v[140:141], v[142:143]
	v_cvt_pk_f16_f32 v136, v136, v137
	v_cvt_pk_f16_f32 v137, v138, v139
	v_and_b32_e32 v138, 0xffff0000, v137
	v_lshlrev_b32_e32 v139, 16, v137
	v_or_b32_sdwa v137, v138, v136 dst_sel:DWORD dst_unused:UNUSED_PAD src0_sel:DWORD src1_sel:WORD_1
	v_or_b32_sdwa v136, v139, v136 dst_sel:DWORD dst_unused:UNUSED_PAD src0_sel:DWORD src1_sel:WORD_0
	ds_write_b64 v0, v[136:137] offset:1280

; __device__ __forceinline__ void dsa_unit(int b, int blk, const bf16_t* P, bf16_t* OB, LAS unsigned char* lds, int wave, int tid_in) {
;     ...
;         for (int kt = wave; kt < ntile; kt += 48) {
; #pragma unroll
;             for (int j = 0; j < 6; ++j) {
;                 const int kc = kt + 8 * j;
;                 if (kc < ntile) {
;                     if (kc + 40 < ntile) { const bf16_t* kp = kp0 + (size_t)(16 * (kc + 40)) * NP_; kf[(j + 5) % 6][0] = *(const bf16x8*)kp; kf[(j + 5) % 6][1] = *(const bf16x8*)(kp + 32); }
;                     f32x4 sc = (f32x4){0.f, 0.f, 0.f, 0.f};
.LBB0_596:
	s_sub_i32 s0, s2, 40
	s_cmp_lt_i32 s0, s3
	s_cselect_b64 s[4:5], -1, 0
	s_and_b64 vcc, exec, s[4:5]
	s_cbranch_vccz .LBB0_598
	s_nop 0
	v_add_co_u32_e32 v106, vcc, 0xffba0000, v130
	s_nop 1
	v_addc_co_u32_e32 v107, vcc, -1, v131, vcc
	global_load_dwordx4 v[110:113], v[106:107], off offset:-64
	s_nop 0
	global_load_dwordx4 v[106:109], v[106:107], off
	s_waitcnt vmcnt(10)
	s_branch .Ls1body_598

; #define LAS __attribute__((address_space(3)))
; #define MFMA16(a, b, c) __builtin_amdgcn_mfma_f32_16x16x32_bf16((a), (b), (c), 0, 0, 0)
; __device__ __forceinline__ void dsa_unit(int b, int blk, const bf16_t* P, bf16_t* OB, LAS unsigned char* lds, int wave, int tid_in) {
;     ...
;             for (int j = 0; j < 6; ++j) {
;                 const int kc = kt + 8 * j;
;                 if (kc < ntile) {
;                     if (kc + 40 < ntile) { const bf16_t* kp = kp0 + (size_t)(16 * (kc + 40)) * NP_; kf[(j + 5) % 6][0] = *(const bf16x8*)kp; kf[(j + 5) % 6][1] = *(const bf16x8*)(kp + 32); }
;                     f32x4 sc = (f32x4){0.f, 0.f, 0.f, 0.f};
; #pragma unroll
;                     for (int h = 0; h < 8; ++h) { f32x4 s = (f32x4){0.f, 0.f, 0.f, 0.f}; s = MFMA16(kf[j][0], bqi[h][0], s); s = MFMA16(kf[j][1], bqi[h][1], s);
; #pragma unroll
;                         for (int e = 0; e < 4; ++e) sc[e] = fmaf(w[h], fmaxf(s[e], 0.f), sc[e]); }
;                     u32x2 o2;
;                     { const _Float16 h0 = (_Float16)sc[0], h1 = (_Float16)sc[1], h2 = (_Float16)sc[2], h3 = (_Float16)sc[3];
;                       o2.x = (unsigned)__builtin_bit_cast(unsigned short, h0) | ((unsigned)__builtin_bit_cast(unsigned short, h1) << 16);
;                       o2.y = (unsigned)__builtin_bit_cast(unsigned short, h2) | ((unsigned)__builtin_bit_cast(unsigned short, h3) << 16); }
;                     *(LAS u32x2*)(lds + qi * C_SCW + (16 * kc + 4 * g4) * 2) = o2;
;                 }
.Ls1body_598:
	s_nop 0
	v_mfma_f32_16x16x32_bf16 v[136:139], v[66:69], v[2:5], 0
	s_add_i32 s0, s2, 0xffffffb8
	s_cmp_ge_i32 s0, s3
	s_nop 0
	v_mfma_f32_16x16x32_bf16 v[136:139], v[70:73], v[6:9], v[136:139]
	v_mfma_f32_16x16x32_bf16 v[140:143], v[66:69], v[10:13], 0
	s_nop 6
	v_max_f32_e32 v136, v136, v136
	v_max_f32_e32 v137, v137, v137
	v_max_f32_e32 v138, v138, v138
	v_max_f32_e32 v136, 0, v136
	v_max_f32_e32 v144, 0, v137
	v_max_f32_e32 v137, 0, v138
	v_pk_fma_f32 v[146:147], v[114:115], v[136:137], 0 op_sel_hi:[1,1,0]
	v_max_f32_e32 v136, v139, v139
	v_max_f32_e32 v145, 0, v136
	v_mfma_f32_16x16x32_bf16 v[136:139], v[70:73], v[14:17], v[140:143]
	s_nop 2
	v_fma_f32 v142, v114, v144, 0
	v_fma_f32 v143, v115, v145, 0
	s_nop 2
	v_max_f32_e32 v136, v136, v136
	v_max_f32_e32 v148, 0, v136
	v_max_f32_e32 v136, v137, v137
	v_max_f32_e32 v140, 0, v136
	v_max_f32_e32 v136, v138, v138
	v_max_f32_e32 v149, 0, v136
	v_max_f32_e32 v141, v139, v139
	v_mfma_f32_16x16x32_bf16 v[136:139], v[66:69], v[18:21], 0
	v_max_f32_e32 v141, 0, v141
	v_pk_fma_f32 v[144:145], v[116:117], v[140:141], v[142:143]
	v_mfma_f32_16x16x32_bf16 v[136:139], v[70:73], v[22:25], v[136:139]
	v_mfma_f32_16x16x32_bf16 v[140:143], v[66:69], v[26:29], 0
	s_nop 6
	v_max_f32_e32 v136, v136, v136
	v_max_f32_e32 v150, 0, v136
	v_max_f32_e32 v136, v137, v137
	v_max_f32_e32 v152, 0, v136
	v_max_f32_e32 v136, v138, v138
	v_max_f32_e32 v151, 0, v136
	v_max_f32_e32 v136, v139, v139
	v_max_f32_e32 v153, 0, v136
	v_mfma_f32_16x16x32_bf16 v[136:139], v[70:73], v[30:33], v[140:143]
	v_mfma_f32_16x16x32_bf16 v[140:143], v[66:69], v[34:37], 0
	s_nop 6
	v_max_f32_e32 v136, v136, v136
	v_max_f32_e32 v154, 0, v136
	v_max_f32_e32 v136, v137, v137
	v_max_f32_e32 v156, 0, v136
	v_max_f32_e32 v136, v138, v138
	v_max_f32_e32 v155, 0, v136
	v_max_f32_e32 v136, v139, v139
	v_max_f32_e32 v157, 0, v136
	v_mfma_f32_16x16x32_bf16 v[136:139], v[70:73], v[38:41], v[140:143]
	v_mfma_f32_16x16x32_bf16 v[140:143], v[66:69], v[42:45], 0
	s_nop 6
	v_max_f32_e32 v136, v136, v136
	v_max_f32_e32 v158, 0, v136
	v_max_f32_e32 v136, v137, v137
	v_max_f32_e32 v160, 0, v136
	v_max_f32_e32 v136, v138, v138
	v_max_f32_e32 v159, 0, v136
	v_max_f32_e32 v136, v139, v139
	v_max_f32_e32 v161, 0, v136
	v_mfma_f32_16x16x32_bf16 v[136:139], v[70:73], v[46:49], v[140:143]
	v_mfma_f32_16x16x32_bf16 v[140:143], v[66:69], v[50:53], 0
	s_nop 6
	v_max_f32_e32 v136, v136, v136
	v_max_f32_e32 v162, 0, v136
	v_max_f32_e32 v136, v137, v137
	v_max_f32_e32 v164, 0, v136
	v_max_f32_e32 v136, v138, v138
	v_max_f32_e32 v163, 0, v136
	v_max_f32_e32 v136, v139, v139
	v_max_f32_e32 v165, 0, v136
	v_mfma_f32_16x16x32_bf16 v[136:139], v[70:73], v[54:57], v[140:143]
	v_mfma_f32_16x16x32_bf16 v[140:143], v[66:69], v[58:61], 0
	s_nop 6
	v_max_f32_e32 v136, v136, v136
	v_max_f32_e32 v166, 0, v136
	v_max_f32_e32 v136, v137, v137
	v_max_f32_e32 v168, 0, v136
	v_max_f32_e32 v136, v138, v138
	v_max_f32_e32 v167, 0, v136
	v_max_f32_e32 v136, v139, v139
	v_max_f32_e32 v169, 0, v136
	v_mfma_f32_16x16x32_bf16 v[136:139], v[70:73], v[62:65], v[140:143]
	s_nop 2
	v_fma_f32 v142, v118, v152, v144
	v_fma_f32 v143, v119, v153, v145
	v_pk_fma_f32 v[142:143], v[120:121], v[156:157], v[142:143]
	s_nop 1
	v_max_f32_e32 v137, v137, v137
	v_max_f32_e32 v140, 0, v137
	v_max_f32_e32 v137, v138, v138
	v_max_f32_e32 v138, v139, v139
	v_max_f32_e32 v141, 0, v138
	v_pk_fma_f32 v[138:139], v[116:117], v[148:149], v[146:147]
	v_pk_fma_f32 v[142:143], v[122:123], v[160:161], v[142:143]
	v_pk_fma_f32 v[138:139], v[118:119], v[150:151], v[138:139]
	v_max_f32_e32 v136, v136, v136
	v_pk_fma_f32 v[138:139], v[120:121], v[154:155], v[138:139]
	v_pk_fma_f32 v[142:143], v[124:125], v[164:165], v[142:143]
	v_pk_fma_f32 v[138:139], v[122:123], v[158:159], v[138:139]
	v_max_f32_e32 v136, 0, v136
	v_pk_fma_f32 v[138:139], v[124:125], v[162:163], v[138:139]
	v_max_f32_e32 v137, 0, v137
	v_pk_fma_f32 v[138:139], v[126:127], v[166:167], v[138:139]
	v_pk_fma_f32 v[142:143], v[126:127], v[168:169], v[142:143]
	v_pk_fma_f32 v[136:137], v[128:129], v[136:137], v[138:139]
	v_pk_fma_f32 v[138:139], v[128:129], v[140:141], v[142:143]
	v_cvt_pk_f16_f32 v136, v136, v137
	v_cvt_pk_f16_f32 v137, v138, v139
	v_and_b32_e32 v138, 0xffff0000, v137
	v_lshlrev_b32_e32 v139, 16, v137
	v_or_b32_sdwa v137, v138, v136 dst_sel:DWORD dst_unused:UNUSED_PAD src0_sel:DWORD src1_sel:WORD_1
	v_or_b32_sdwa v136, v139, v136 dst_sel:DWORD dst_unused:UNUSED_PAD src0_sel:DWORD src1_sel:WORD_0
	ds_write_b64 v0, v[136:137]
	s_cbranch_scc1 .LBB0_607
	s_sub_i32 s0, s2, 32
	s_cmp_ge_i32 s0, s3
	s_cbranch_scc1 .LBB0_601
	v_add_co_u32_e32 v70, vcc, 0xffc80000, v130
	s_nop 1
	v_addc_co_u32_e32 v71, vcc, -1, v131, vcc
	global_load_dwordx4 v[66:69], v[70:71], off offset:-64
	s_nop 0
	global_load_dwordx4 v[70:73], v[70:71], off
	s_waitcnt vmcnt(10)
	s_branch .Ls1body_601
; #define LAS __attribute__((address_space(3)))
; #define MFMA16(a, b, c) __builtin_amdgcn_mfma_f32_16x16x32_bf16((a), (b), (c), 0, 0, 0)
; __device__ __forceinline__ void dsa_unit(int b, int blk, const bf16_t* P, bf16_t* OB, LAS unsigned char* lds, int wave, int tid_in) {
;     ...
;             for (int j = 0; j < 6; ++j) {
;                 const int kc = kt + 8 * j;
;                 if (kc < ntile) {
;                     if (kc + 40 < ntile) { const bf16_t* kp = kp0 + (size_t)(16 * (kc + 40)) * NP_; kf[(j + 5) % 6][0] = *(const bf16x8*)kp; kf[(j + 5) % 6][1] = *(const bf16x8*)(kp + 32); }
;                     f32x4 sc = (f32x4){0.f, 0.f, 0.f, 0.f};
; #pragma unroll
;                     for (int h = 0; h < 8; ++h) { f32x4 s = (f32x4){0.f, 0.f, 0.f, 0.f}; s = MFMA16(kf[j][0], bqi[h][0], s); s = MFMA16(kf[j][1], bqi[h][1], s);
; #pragma unroll
;                         for (int e = 0; e < 4; ++e) sc[e] = fmaf(w[h], fmaxf(s[e], 0.f), sc[e]); }
;                     u32x2 o2;
;                     { const _Float16 h0 = (_Float16)sc[0], h1 = (_Float16)sc[1], h2 = (_Float16)sc[2], h3 = (_Float16)sc[3];
;                       o2.x = (unsigned)__builtin_bit_cast(unsigned short, h0) | ((unsigned)__builtin_bit_cast(unsigned short, h1) << 16);
;                       o2.y = (unsigned)__builtin_bit_cast(unsigned short, h2) | ((unsigned)__builtin_bit_cast(unsigned short, h3) << 16); }
;                     *(LAS u32x2*)(lds + qi * C_SCW + (16 * kc + 4 * g4) * 2) = o2;
;                 }
.LBB0_601:
	s_waitcnt vmcnt(0)
.Ls1body_601:
	v_mfma_f32_16x16x32_bf16 v[136:139], v[74:77], v[2:5], 0
	v_mfma_f32_16x16x32_bf16 v[136:139], v[78:81], v[6:9], v[136:139]
	v_mfma_f32_16x16x32_bf16 v[140:143], v[74:77], v[10:13], 0
	s_nop 6
	v_max_f32_e32 v136, v136, v136
	v_max_f32_e32 v137, v137, v137
	v_max_f32_e32 v138, v138, v138
	v_max_f32_e32 v136, 0, v136
	v_max_f32_e32 v144, 0, v137
	v_max_f32_e32 v137, 0, v138
	v_pk_fma_f32 v[146:147], v[114:115], v[136:137], 0 op_sel_hi:[1,1,0]
	v_max_f32_e32 v136, v139, v139
	v_max_f32_e32 v145, 0, v136
	v_mfma_f32_16x16x32_bf16 v[136:139], v[78:81], v[14:17], v[140:143]
	s_nop 2
	v_fma_f32 v142, v114, v144, 0
	v_fma_f32 v143, v115, v145, 0
	s_nop 2
	v_max_f32_e32 v136, v136, v136
	v_max_f32_e32 v148, 0, v136
	v_max_f32_e32 v136, v137, v137
	v_max_f32_e32 v140, 0, v136
	v_max_f32_e32 v136, v138, v138
	v_max_f32_e32 v149, 0, v136
	v_max_f32_e32 v141, v139, v139
	v_mfma_f32_16x16x32_bf16 v[136:139], v[74:77], v[18:21], 0
	v_max_f32_e32 v141, 0, v141
	v_pk_fma_f32 v[144:145], v[116:117], v[140:141], v[142:143]
	v_mfma_f32_16x16x32_bf16 v[136:139], v[78:81], v[22:25], v[136:139]
	v_mfma_f32_16x16x32_bf16 v[140:143], v[74:77], v[26:29], 0
	s_nop 6
	v_max_f32_e32 v136, v136, v136
	v_max_f32_e32 v150, 0, v136
	v_max_f32_e32 v136, v137, v137
	v_max_f32_e32 v152, 0, v136
	v_max_f32_e32 v136, v138, v138
	v_max_f32_e32 v151, 0, v136
	v_max_f32_e32 v136, v139, v139
	v_max_f32_e32 v153, 0, v136
	v_mfma_f32_16x16x32_bf16 v[136:139], v[78:81], v[30:33], v[140:143]
	v_mfma_f32_16x16x32_bf16 v[140:143], v[74:77], v[34:37], 0
	s_nop 6
	v_max_f32_e32 v136, v136, v136
	v_max_f32_e32 v154, 0, v136
	v_max_f32_e32 v136, v137, v137
	v_max_f32_e32 v156, 0, v136
	v_max_f32_e32 v136, v138, v138
	v_max_f32_e32 v155, 0, v136
	v_max_f32_e32 v136, v139, v139
	v_max_f32_e32 v157, 0, v136
	v_mfma_f32_16x16x32_bf16 v[136:139], v[78:81], v[38:41], v[140:143]
	v_mfma_f32_16x16x32_bf16 v[140:143], v[74:77], v[42:45], 0
	s_nop 6
	v_max_f32_e32 v136, v136, v136
	v_max_f32_e32 v158, 0, v136
	v_max_f32_e32 v136, v137, v137
	v_max_f32_e32 v160, 0, v136
	v_max_f32_e32 v136, v138, v138
	v_max_f32_e32 v159, 0, v136
	v_max_f32_e32 v136, v139, v139
	v_max_f32_e32 v161, 0, v136
	v_mfma_f32_16x16x32_bf16 v[136:139], v[78:81], v[46:49], v[140:143]
	v_mfma_f32_16x16x32_bf16 v[140:143], v[74:77], v[50:53], 0
	s_nop 6
	v_max_f32_e32 v136, v136, v136
	v_max_f32_e32 v162, 0, v136
	v_max_f32_e32 v136, v137, v137
	v_max_f32_e32 v164, 0, v136
	v_max_f32_e32 v136, v138, v138
	v_max_f32_e32 v163, 0, v136
	v_max_f32_e32 v136, v139, v139
	v_max_f32_e32 v165, 0, v136
	v_mfma_f32_16x16x32_bf16 v[136:139], v[78:81], v[54:57], v[140:143]
	v_mfma_f32_16x16x32_bf16 v[140:143], v[74:77], v[58:61], 0
	s_nop 6
	v_max_f32_e32 v136, v136, v136
	v_max_f32_e32 v166, 0, v136
	v_max_f32_e32 v136, v137, v137
	v_max_f32_e32 v168, 0, v136
	v_max_f32_e32 v136, v138, v138
	v_max_f32_e32 v167, 0, v136
	v_max_f32_e32 v136, v139, v139
	v_max_f32_e32 v169, 0, v136
	v_mfma_f32_16x16x32_bf16 v[136:139], v[78:81], v[62:65], v[140:143]
	s_nop 2
	v_fma_f32 v142, v118, v152, v144
	v_fma_f32 v143, v119, v153, v145
	v_pk_fma_f32 v[142:143], v[120:121], v[156:157], v[142:143]
	s_nop 1
	v_max_f32_e32 v137, v137, v137
	v_max_f32_e32 v140, 0, v137
	v_max_f32_e32 v137, v138, v138
	v_max_f32_e32 v138, v139, v139
	v_max_f32_e32 v141, 0, v138
	v_pk_fma_f32 v[138:139], v[116:117], v[148:149], v[146:147]
	v_pk_fma_f32 v[142:143], v[122:123], v[160:161], v[142:143]
	v_pk_fma_f32 v[138:139], v[118:119], v[150:151], v[138:139]
	v_max_f32_e32 v136, v136, v136
	v_pk_fma_f32 v[138:139], v[120:121], v[154:155], v[138:139]
	v_pk_fma_f32 v[142:143], v[124:125], v[164:165], v[142:143]
	v_pk_fma_f32 v[138:139], v[122:123], v[158:159], v[138:139]
	v_max_f32_e32 v136, 0, v136
	v_pk_fma_f32 v[138:139], v[124:125], v[162:163], v[138:139]
	v_max_f32_e32 v137, 0, v137
	v_pk_fma_f32 v[138:139], v[126:127], v[166:167], v[138:139]
	v_pk_fma_f32 v[142:143], v[126:127], v[168:169], v[142:143]
	v_pk_fma_f32 v[136:137], v[128:129], v[136:137], v[138:139]
	v_pk_fma_f32 v[138:139], v[128:129], v[140:141], v[142:143]
	v_cvt_pk_f16_f32 v136, v136, v137
	v_cvt_pk_f16_f32 v137, v138, v139
	v_and_b32_e32 v138, 0xffff0000, v137
	v_lshlrev_b32_e32 v139, 16, v137
	v_or_b32_sdwa v137, v138, v136 dst_sel:DWORD dst_unused:UNUSED_PAD src0_sel:DWORD src1_sel:WORD_1
	v_or_b32_sdwa v136, v139, v136 dst_sel:DWORD dst_unused:UNUSED_PAD src0_sel:DWORD src1_sel:WORD_0
	ds_write_b64 v0, v[136:137] offset:256
	s_sub_i32 s0, s2, 64
	s_cmp_ge_i32 s0, s3
	s_cbranch_scc0 .LBB0_608

; #define LAS __attribute__((address_space(3)))
; #define MFMA16(a, b, c) __builtin_amdgcn_mfma_f32_16x16x32_bf16((a), (b), (c), 0, 0, 0)
; __device__ __forceinline__ void dsa_unit(int b, int blk, const bf16_t* P, bf16_t* OB, LAS unsigned char* lds, int wave, int tid_in) {
;     ...
;             for (int j = 0; j < 6; ++j) {
;                 const int kc = kt + 8 * j;
;                 if (kc < ntile) {
;                     if (kc + 40 < ntile) { const bf16_t* kp = kp0 + (size_t)(16 * (kc + 40)) * NP_; kf[(j + 5) % 6][0] = *(const bf16x8*)kp; kf[(j + 5) % 6][1] = *(const bf16x8*)(kp + 32); }
;                     f32x4 sc = (f32x4){0.f, 0.f, 0.f, 0.f};
; #pragma unroll
;                     for (int h = 0; h < 8; ++h) { f32x4 s = (f32x4){0.f, 0.f, 0.f, 0.f}; s = MFMA16(kf[j][0], bqi[h][0], s); s = MFMA16(kf[j][1], bqi[h][1], s);
; #pragma unroll
;                         for (int e = 0; e < 4; ++e) sc[e] = fmaf(w[h], fmaxf(s[e], 0.f), sc[e]); }
;                     u32x2 o2;
;                     { const _Float16 h0 = (_Float16)sc[0], h1 = (_Float16)sc[1], h2 = (_Float16)sc[2], h3 = (_Float16)sc[3];
;                       o2.x = (unsigned)__builtin_bit_cast(unsigned short, h0) | ((unsigned)__builtin_bit_cast(unsigned short, h1) << 16);
;                       o2.y = (unsigned)__builtin_bit_cast(unsigned short, h2) | ((unsigned)__builtin_bit_cast(unsigned short, h3) << 16); }
;                     *(LAS u32x2*)(lds + qi * C_SCW + (16 * kc + 4 * g4) * 2) = o2;
;                 }
.LBB0_603:
	s_add_i32 s0, s2, -16
	s_cmp_ge_i32 s0, s3
	s_cbranch_scc1 .LBB0_605
	v_add_co_u32_e32 v86, vcc, 0xffe40000, v130
	s_nop 1
	v_addc_co_u32_e32 v87, vcc, -1, v131, vcc
	global_load_dwordx4 v[82:85], v[86:87], off offset:-64
	s_nop 0
	global_load_dwordx4 v[86:89], v[86:87], off
	s_waitcnt vmcnt(10)
	s_branch .Ls1body_605
.LBB0_605:
	s_waitcnt vmcnt(0)
.Ls1body_605:
	v_mfma_f32_16x16x32_bf16 v[136:139], v[90:93], v[2:5], 0
	v_mfma_f32_16x16x32_bf16 v[136:139], v[94:97], v[6:9], v[136:139]
	v_mfma_f32_16x16x32_bf16 v[140:143], v[90:93], v[10:13], 0
	s_nop 6
	v_max_f32_e32 v136, v136, v136
	v_max_f32_e32 v137, v137, v137
	v_max_f32_e32 v138, v138, v138
	v_max_f32_e32 v136, 0, v136
	v_max_f32_e32 v144, 0, v137
	v_max_f32_e32 v137, 0, v138
	v_pk_fma_f32 v[146:147], v[114:115], v[136:137], 0 op_sel_hi:[1,1,0]
	v_max_f32_e32 v136, v139, v139
	v_max_f32_e32 v145, 0, v136
	v_mfma_f32_16x16x32_bf16 v[136:139], v[94:97], v[14:17], v[140:143]
	s_nop 2
	v_fma_f32 v142, v114, v144, 0
	v_fma_f32 v143, v115, v145, 0
	s_nop 2
	v_max_f32_e32 v136, v136, v136
	v_max_f32_e32 v148, 0, v136
	v_max_f32_e32 v136, v137, v137
	v_max_f32_e32 v140, 0, v136
	v_max_f32_e32 v136, v138, v138
	v_max_f32_e32 v149, 0, v136
	v_max_f32_e32 v141, v139, v139
	v_mfma_f32_16x16x32_bf16 v[136:139], v[90:93], v[18:21], 0
	v_max_f32_e32 v141, 0, v141
	v_pk_fma_f32 v[144:145], v[116:117], v[140:141], v[142:143]
	v_mfma_f32_16x16x32_bf16 v[136:139], v[94:97], v[22:25], v[136:139]
	v_mfma_f32_16x16x32_bf16 v[140:143], v[90:93], v[26:29], 0
	s_nop 6
	v_max_f32_e32 v136, v136, v136
	v_max_f32_e32 v150, 0, v136
	v_max_f32_e32 v136, v137, v137
	v_max_f32_e32 v152, 0, v136
	v_max_f32_e32 v136, v138, v138
	v_max_f32_e32 v151, 0, v136
	v_max_f32_e32 v136, v139, v139
	v_max_f32_e32 v153, 0, v136
	v_mfma_f32_16x16x32_bf16 v[136:139], v[94:97], v[30:33], v[140:143]
	v_mfma_f32_16x16x32_bf16 v[140:143], v[90:93], v[34:37], 0
	s_nop 6
	v_max_f32_e32 v136, v136, v136
	v_max_f32_e32 v154, 0, v136
	v_max_f32_e32 v136, v137, v137
	v_max_f32_e32 v156, 0, v136
	v_max_f32_e32 v136, v138, v138
	v_max_f32_e32 v155, 0, v136
	v_max_f32_e32 v136, v139, v139
	v_max_f32_e32 v157, 0, v136
	v_mfma_f32_16x16x32_bf16 v[136:139], v[94:97], v[38:41], v[140:143]
	v_mfma_f32_16x16x32_bf16 v[140:143], v[90:93], v[42:45], 0
	s_nop 6
	v_max_f32_e32 v136, v136, v136
	v_max_f32_e32 v158, 0, v136
	v_max_f32_e32 v136, v137, v137
	v_max_f32_e32 v160, 0, v136
	v_max_f32_e32 v136, v138, v138
	v_max_f32_e32 v159, 0, v136
	v_max_f32_e32 v136, v139, v139
	v_max_f32_e32 v161, 0, v136
	v_mfma_f32_16x16x32_bf16 v[136:139], v[94:97], v[46:49], v[140:143]
	v_mfma_f32_16x16x32_bf16 v[140:143], v[90:93], v[50:53], 0
	s_nop 6
	v_max_f32_e32 v136, v136, v136
	v_max_f32_e32 v162, 0, v136
	v_max_f32_e32 v136, v137, v137
	v_max_f32_e32 v164, 0, v136
	v_max_f32_e32 v136, v138, v138
	v_max_f32_e32 v163, 0, v136
	v_max_f32_e32 v136, v139, v139
	v_max_f32_e32 v165, 0, v136
	v_mfma_f32_16x16x32_bf16 v[136:139], v[94:97], v[54:57], v[140:143]
	v_mfma_f32_16x16x32_bf16 v[140:143], v[90:93], v[58:61], 0
	s_nop 6
	v_max_f32_e32 v136, v136, v136
	v_max_f32_e32 v166, 0, v136
	v_max_f32_e32 v136, v137, v137
	v_max_f32_e32 v168, 0, v136
	v_max_f32_e32 v136, v138, v138
	v_max_f32_e32 v167, 0, v136
	v_max_f32_e32 v136, v139, v139
	v_max_f32_e32 v169, 0, v136
	v_mfma_f32_16x16x32_bf16 v[136:139], v[94:97], v[62:65], v[140:143]
	s_nop 2
	v_fma_f32 v142, v118, v152, v144
	v_fma_f32 v143, v119, v153, v145
	v_pk_fma_f32 v[142:143], v[120:121], v[156:157], v[142:143]
	s_nop 1
	v_max_f32_e32 v137, v137, v137
	v_max_f32_e32 v140, 0, v137
	v_max_f32_e32 v137, v138, v138
	v_max_f32_e32 v138, v139, v139
	v_max_f32_e32 v141, 0, v138
	v_pk_fma_f32 v[138:139], v[116:117], v[148:149], v[146:147]
	v_pk_fma_f32 v[142:143], v[122:123], v[160:161], v[142:143]
	v_pk_fma_f32 v[138:139], v[118:119], v[150:151], v[138:139]
	v_max_f32_e32 v136, v136, v136
	v_pk_fma_f32 v[138:139], v[120:121], v[154:155], v[138:139]
	v_pk_fma_f32 v[142:143], v[124:125], v[164:165], v[142:143]
	v_pk_fma_f32 v[138:139], v[122:123], v[158:159], v[138:139]
	v_max_f32_e32 v136, 0, v136
	v_pk_fma_f32 v[138:139], v[124:125], v[162:163], v[138:139]
	v_max_f32_e32 v137, 0, v137
	v_pk_fma_f32 v[138:139], v[126:127], v[166:167], v[138:139]
	v_pk_fma_f32 v[142:143], v[126:127], v[168:169], v[142:143]
	v_pk_fma_f32 v[136:137], v[128:129], v[136:137], v[138:139]
	v_pk_fma_f32 v[138:139], v[128:129], v[140:141], v[142:143]
	v_cvt_pk_f16_f32 v136, v136, v137
	v_cvt_pk_f16_f32 v137, v138, v139
	v_and_b32_e32 v138, 0xffff0000, v137
	v_lshlrev_b32_e32 v139, 16, v137
	v_or_b32_sdwa v137, v138, v136 dst_sel:DWORD dst_unused:UNUSED_PAD src0_sel:DWORD src1_sel:WORD_1
	v_or_b32_sdwa v136, v139, v136 dst_sel:DWORD dst_unused:UNUSED_PAD src0_sel:DWORD src1_sel:WORD_0
	ds_write_b64 v0, v[136:137] offset:768
	s_sub_i32 s0, s2, 48
	s_cmp_ge_i32 s0, s3
	s_cbranch_scc0 .LBB0_612

; #define LAS __attribute__((address_space(3)))
; #define MFMA16(a, b, c) __builtin_amdgcn_mfma_f32_16x16x32_bf16((a), (b), (c), 0, 0, 0)
; __device__ __forceinline__ void dsa_unit(int b, int blk, const bf16_t* P, bf16_t* OB, LAS unsigned char* lds, int wave, int tid_in) {
;     ...
;             for (int j = 0; j < 6; ++j) {
;                 const int kc = kt + 8 * j;
;                 if (kc < ntile) {
;                     if (kc + 40 < ntile) { const bf16_t* kp = kp0 + (size_t)(16 * (kc + 40)) * NP_; kf[(j + 5) % 6][0] = *(const bf16x8*)kp; kf[(j + 5) % 6][1] = *(const bf16x8*)(kp + 32); }
;                     f32x4 sc = (f32x4){0.f, 0.f, 0.f, 0.f};
; #pragma unroll
;                     for (int h = 0; h < 8; ++h) { f32x4 s = (f32x4){0.f, 0.f, 0.f, 0.f}; s = MFMA16(kf[j][0], bqi[h][0], s); s = MFMA16(kf[j][1], bqi[h][1], s);
; #pragma unroll
;                         for (int e = 0; e < 4; ++e) sc[e] = fmaf(w[h], fmaxf(s[e], 0.f), sc[e]); }
;                     u32x2 o2;
;                     { const _Float16 h0 = (_Float16)sc[0], h1 = (_Float16)sc[1], h2 = (_Float16)sc[2], h3 = (_Float16)sc[3];
;                       o2.x = (unsigned)__builtin_bit_cast(unsigned short, h0) | ((unsigned)__builtin_bit_cast(unsigned short, h1) << 16);
;                       o2.y = (unsigned)__builtin_bit_cast(unsigned short, h2) | ((unsigned)__builtin_bit_cast(unsigned short, h3) << 16); }
;                     *(LAS u32x2*)(lds + qi * C_SCW + (16 * kc + 4 * g4) * 2) = o2;
;                 }
.LBB0_608:
	s_sub_i32 s0, s2, 24
	s_cmp_ge_i32 s0, s3
	s_cbranch_scc1 .LBB0_610
	v_add_co_u32_e32 v78, vcc, 0xffd60000, v130
	s_nop 1
	v_addc_co_u32_e32 v79, vcc, -1, v131, vcc
	global_load_dwordx4 v[74:77], v[78:79], off offset:-64
	s_nop 0
	global_load_dwordx4 v[78:81], v[78:79], off
	s_waitcnt vmcnt(10)
	s_branch .Ls1body_610
.LBB0_610:
	s_waitcnt vmcnt(0)
.Ls1body_610:
	v_mfma_f32_16x16x32_bf16 v[136:139], v[82:85], v[2:5], 0
	v_mfma_f32_16x16x32_bf16 v[136:139], v[86:89], v[6:9], v[136:139]
	v_mfma_f32_16x16x32_bf16 v[140:143], v[82:85], v[10:13], 0
	s_nop 6
	v_max_f32_e32 v136, v136, v136
	v_max_f32_e32 v137, v137, v137
	v_max_f32_e32 v138, v138, v138
	v_max_f32_e32 v136, 0, v136
	v_max_f32_e32 v144, 0, v137
	v_max_f32_e32 v137, 0, v138
	v_pk_fma_f32 v[146:147], v[114:115], v[136:137], 0 op_sel_hi:[1,1,0]
	v_max_f32_e32 v136, v139, v139
	v_max_f32_e32 v145, 0, v136
	v_mfma_f32_16x16x32_bf16 v[136:139], v[86:89], v[14:17], v[140:143]
	s_nop 2
	v_fma_f32 v142, v114, v144, 0
	v_fma_f32 v143, v115, v145, 0
	s_nop 2
	v_max_f32_e32 v136, v136, v136
	v_max_f32_e32 v148, 0, v136
	v_max_f32_e32 v136, v137, v137
	v_max_f32_e32 v140, 0, v136
	v_max_f32_e32 v136, v138, v138
	v_max_f32_e32 v149, 0, v136
	v_max_f32_e32 v141, v139, v139
	v_mfma_f32_16x16x32_bf16 v[136:139], v[82:85], v[18:21], 0
	v_max_f32_e32 v141, 0, v141
	v_pk_fma_f32 v[144:145], v[116:117], v[140:141], v[142:143]
	v_mfma_f32_16x16x32_bf16 v[136:139], v[86:89], v[22:25], v[136:139]
	v_mfma_f32_16x16x32_bf16 v[140:143], v[82:85], v[26:29], 0
	s_nop 6
	v_max_f32_e32 v136, v136, v136
	v_max_f32_e32 v150, 0, v136
	v_max_f32_e32 v136, v137, v137
	v_max_f32_e32 v152, 0, v136
	v_max_f32_e32 v136, v138, v138
	v_max_f32_e32 v151, 0, v136
	v_max_f32_e32 v136, v139, v139
	v_max_f32_e32 v153, 0, v136
	v_mfma_f32_16x16x32_bf16 v[136:139], v[86:89], v[30:33], v[140:143]
	v_mfma_f32_16x16x32_bf16 v[140:143], v[82:85], v[34:37], 0
	s_nop 6
	v_max_f32_e32 v136, v136, v136
	v_max_f32_e32 v154, 0, v136
	v_max_f32_e32 v136, v137, v137
	v_max_f32_e32 v156, 0, v136
	v_max_f32_e32 v136, v138, v138
	v_max_f32_e32 v155, 0, v136
	v_max_f32_e32 v136, v139, v139
	v_max_f32_e32 v157, 0, v136
	v_mfma_f32_16x16x32_bf16 v[136:139], v[86:89], v[38:41], v[140:143]
	v_mfma_f32_16x16x32_bf16 v[140:143], v[82:85], v[42:45], 0
	s_nop 6
	v_max_f32_e32 v136, v136, v136
	v_max_f32_e32 v158, 0, v136
	v_max_f32_e32 v136, v137, v137
	v_max_f32_e32 v160, 0, v136
	v_max_f32_e32 v136, v138, v138
	v_max_f32_e32 v159, 0, v136
	v_max_f32_e32 v136, v139, v139
	v_max_f32_e32 v161, 0, v136
	v_mfma_f32_16x16x32_bf16 v[136:139], v[86:89], v[46:49], v[140:143]
	v_mfma_f32_16x16x32_bf16 v[140:143], v[82:85], v[50:53], 0
	s_nop 6
	v_max_f32_e32 v136, v136, v136
	v_max_f32_e32 v162, 0, v136
	v_max_f32_e32 v136, v137, v137
	v_max_f32_e32 v164, 0, v136
	v_max_f32_e32 v136, v138, v138
	v_max_f32_e32 v163, 0, v136
	v_max_f32_e32 v136, v139, v139
	v_max_f32_e32 v165, 0, v136
	v_mfma_f32_16x16x32_bf16 v[136:139], v[86:89], v[54:57], v[140:143]
	v_mfma_f32_16x16x32_bf16 v[140:143], v[82:85], v[58:61], 0
	s_nop 6
	v_max_f32_e32 v136, v136, v136
	v_max_f32_e32 v166, 0, v136
	v_max_f32_e32 v136, v137, v137
	v_max_f32_e32 v168, 0, v136
	v_max_f32_e32 v136, v138, v138
	v_max_f32_e32 v167, 0, v136
	v_max_f32_e32 v136, v139, v139
	v_max_f32_e32 v169, 0, v136
	v_mfma_f32_16x16x32_bf16 v[136:139], v[86:89], v[62:65], v[140:143]
	s_nop 2
	v_fma_f32 v142, v118, v152, v144
	v_fma_f32 v143, v119, v153, v145
	v_pk_fma_f32 v[142:143], v[120:121], v[156:157], v[142:143]
	s_nop 1
	v_max_f32_e32 v137, v137, v137
	v_max_f32_e32 v140, 0, v137
	v_max_f32_e32 v137, v138, v138
	v_max_f32_e32 v138, v139, v139
	v_max_f32_e32 v141, 0, v138
	v_pk_fma_f32 v[138:139], v[116:117], v[148:149], v[146:147]
	v_pk_fma_f32 v[142:143], v[122:123], v[160:161], v[142:143]
	v_pk_fma_f32 v[138:139], v[118:119], v[150:151], v[138:139]
	v_max_f32_e32 v136, v136, v136
	v_pk_fma_f32 v[138:139], v[120:121], v[154:155], v[138:139]
	v_pk_fma_f32 v[142:143], v[124:125], v[164:165], v[142:143]
	v_pk_fma_f32 v[138:139], v[122:123], v[158:159], v[138:139]
	v_max_f32_e32 v136, 0, v136
	v_pk_fma_f32 v[138:139], v[124:125], v[162:163], v[138:139]
	v_max_f32_e32 v137, 0, v137
	v_pk_fma_f32 v[138:139], v[126:127], v[166:167], v[138:139]
	v_pk_fma_f32 v[142:143], v[126:127], v[168:169], v[142:143]
	v_pk_fma_f32 v[136:137], v[128:129], v[136:137], v[138:139]
	v_pk_fma_f32 v[138:139], v[128:129], v[140:141], v[142:143]
	v_cvt_pk_f16_f32 v136, v136, v137
	v_cvt_pk_f16_f32 v137, v138, v139
	v_and_b32_e32 v138, 0xffff0000, v137
	v_lshlrev_b32_e32 v139, 16, v137
	v_or_b32_sdwa v137, v138, v136 dst_sel:DWORD dst_unused:UNUSED_PAD src0_sel:DWORD src1_sel:WORD_1
	v_or_b32_sdwa v136, v139, v136 dst_sel:DWORD dst_unused:UNUSED_PAD src0_sel:DWORD src1_sel:WORD_0
	ds_write_b64 v0, v[136:137] offset:512
	s_sub_i32 s0, s2, 56
	s_cmp_ge_i32 s0, s3
	s_cbranch_scc0 .LBB0_603

; #define LAS __attribute__((address_space(3)))
; #define MFMA16(a, b, c) __builtin_amdgcn_mfma_f32_16x16x32_bf16((a), (b), (c), 0, 0, 0)
; __device__ __forceinline__ void dsa_unit(int b, int blk, const bf16_t* P, bf16_t* OB, LAS unsigned char* lds, int wave, int tid_in) {
;     ...
;             for (int j = 0; j < 6; ++j) {
;                 const int kc = kt + 8 * j;
;                 if (kc < ntile) {
;                     if (kc + 40 < ntile) { const bf16_t* kp = kp0 + (size_t)(16 * (kc + 40)) * NP_; kf[(j + 5) % 6][0] = *(const bf16x8*)kp; kf[(j + 5) % 6][1] = *(const bf16x8*)(kp + 32); }
;                     f32x4 sc = (f32x4){0.f, 0.f, 0.f, 0.f};
; #pragma unroll
;                     for (int h = 0; h < 8; ++h) { f32x4 s = (f32x4){0.f, 0.f, 0.f, 0.f}; s = MFMA16(kf[j][0], bqi[h][0], s); s = MFMA16(kf[j][1], bqi[h][1], s);
; #pragma unroll
;                         for (int e = 0; e < 4; ++e) sc[e] = fmaf(w[h], fmaxf(s[e], 0.f), sc[e]); }
;                     u32x2 o2;
;                     { const _Float16 h0 = (_Float16)sc[0], h1 = (_Float16)sc[1], h2 = (_Float16)sc[2], h3 = (_Float16)sc[3];
;                       o2.x = (unsigned)__builtin_bit_cast(unsigned short, h0) | ((unsigned)__builtin_bit_cast(unsigned short, h1) << 16);
;                       o2.y = (unsigned)__builtin_bit_cast(unsigned short, h2) | ((unsigned)__builtin_bit_cast(unsigned short, h3) << 16); }
;                     *(LAS u32x2*)(lds + qi * C_SCW + (16 * kc + 4 * g4) * 2) = o2;
;                 }
.LBB0_612:
	s_add_i32 s0, s2, -8
	s_cmp_ge_i32 s0, s3
	s_cbranch_scc1 .LBB0_614
	v_add_co_u32_e32 v94, vcc, 0xfff20000, v130
	s_nop 1
	v_addc_co_u32_e32 v95, vcc, -1, v131, vcc
	global_load_dwordx4 v[90:93], v[94:95], off offset:-64
	s_nop 0
	global_load_dwordx4 v[94:97], v[94:95], off
	s_waitcnt vmcnt(10)
	s_branch .Ls1body_614
.LBB0_614:
	s_waitcnt vmcnt(0)
.Ls1body_614:
	v_mfma_f32_16x16x32_bf16 v[136:139], v[98:101], v[2:5], 0
	v_mfma_f32_16x16x32_bf16 v[136:139], v[102:105], v[6:9], v[136:139]
	v_mfma_f32_16x16x32_bf16 v[140:143], v[98:101], v[10:13], 0
	s_nop 6
	v_max_f32_e32 v136, v136, v136
	v_max_f32_e32 v137, v137, v137
	v_max_f32_e32 v138, v138, v138
	v_max_f32_e32 v136, 0, v136
	v_max_f32_e32 v144, 0, v137
	v_max_f32_e32 v137, 0, v138
	v_pk_fma_f32 v[146:147], v[114:115], v[136:137], 0 op_sel_hi:[1,1,0]
	v_max_f32_e32 v136, v139, v139
	v_max_f32_e32 v145, 0, v136
	v_mfma_f32_16x16x32_bf16 v[136:139], v[102:105], v[14:17], v[140:143]
	s_nop 2
	v_fma_f32 v142, v114, v144, 0
	v_fma_f32 v143, v115, v145, 0
	s_nop 2
	v_max_f32_e32 v136, v136, v136
	v_max_f32_e32 v148, 0, v136
	v_max_f32_e32 v136, v137, v137
	v_max_f32_e32 v140, 0, v136
	v_max_f32_e32 v136, v138, v138
	v_max_f32_e32 v149, 0, v136
	v_max_f32_e32 v141, v139, v139
	v_mfma_f32_16x16x32_bf16 v[136:139], v[98:101], v[18:21], 0
	v_max_f32_e32 v141, 0, v141
	v_pk_fma_f32 v[144:145], v[116:117], v[140:141], v[142:143]
	v_mfma_f32_16x16x32_bf16 v[136:139], v[102:105], v[22:25], v[136:139]
	v_mfma_f32_16x16x32_bf16 v[140:143], v[98:101], v[26:29], 0
	s_nop 6
	v_max_f32_e32 v136, v136, v136
	v_max_f32_e32 v150, 0, v136
	v_max_f32_e32 v136, v137, v137
	v_max_f32_e32 v152, 0, v136
	v_max_f32_e32 v136, v138, v138
	v_max_f32_e32 v151, 0, v136
	v_max_f32_e32 v136, v139, v139
	v_max_f32_e32 v153, 0, v136
	v_mfma_f32_16x16x32_bf16 v[136:139], v[102:105], v[30:33], v[140:143]
	v_mfma_f32_16x16x32_bf16 v[140:143], v[98:101], v[34:37], 0
	s_nop 6
	v_max_f32_e32 v136, v136, v136
	v_max_f32_e32 v154, 0, v136
	v_max_f32_e32 v136, v137, v137
	v_max_f32_e32 v156, 0, v136
	v_max_f32_e32 v136, v138, v138
	v_max_f32_e32 v155, 0, v136
	v_max_f32_e32 v136, v139, v139
	v_max_f32_e32 v157, 0, v136
	v_mfma_f32_16x16x32_bf16 v[136:139], v[102:105], v[38:41], v[140:143]
	v_mfma_f32_16x16x32_bf16 v[140:143], v[98:101], v[42:45], 0
	s_nop 6
	v_max_f32_e32 v136, v136, v136
	v_max_f32_e32 v158, 0, v136
	v_max_f32_e32 v136, v137, v137
	v_max_f32_e32 v160, 0, v136
	v_max_f32_e32 v136, v138, v138
	v_max_f32_e32 v159, 0, v136
	v_max_f32_e32 v136, v139, v139
	v_max_f32_e32 v161, 0, v136
	v_mfma_f32_16x16x32_bf16 v[136:139], v[102:105], v[46:49], v[140:143]
	v_mfma_f32_16x16x32_bf16 v[140:143], v[98:101], v[50:53], 0
	s_nop 6
	v_max_f32_e32 v136, v136, v136
	v_max_f32_e32 v162, 0, v136
	v_max_f32_e32 v136, v137, v137
	v_max_f32_e32 v164, 0, v136
	v_max_f32_e32 v136, v138, v138
	v_max_f32_e32 v163, 0, v136
	v_max_f32_e32 v136, v139, v139
	v_max_f32_e32 v165, 0, v136
	v_mfma_f32_16x16x32_bf16 v[136:139], v[102:105], v[54:57], v[140:143]
	v_mfma_f32_16x16x32_bf16 v[140:143], v[98:101], v[58:61], 0
	s_nop 6
	v_max_f32_e32 v136, v136, v136
	v_max_f32_e32 v166, 0, v136
	v_max_f32_e32 v136, v137, v137
	v_max_f32_e32 v168, 0, v136
	v_max_f32_e32 v136, v138, v138
	v_max_f32_e32 v167, 0, v136
	v_max_f32_e32 v136, v139, v139
	v_max_f32_e32 v169, 0, v136
	v_mfma_f32_16x16x32_bf16 v[136:139], v[102:105], v[62:65], v[140:143]
	s_nop 2
	v_fma_f32 v142, v118, v152, v144
	v_fma_f32 v143, v119, v153, v145
	v_pk_fma_f32 v[142:143], v[120:121], v[156:157], v[142:143]
	s_nop 1
	v_max_f32_e32 v137, v137, v137
	v_max_f32_e32 v140, 0, v137
	v_max_f32_e32 v137, v138, v138
	v_max_f32_e32 v138, v139, v139
	v_max_f32_e32 v141, 0, v138
	v_pk_fma_f32 v[138:139], v[116:117], v[148:149], v[146:147]
	v_pk_fma_f32 v[142:143], v[122:123], v[160:161], v[142:143]
	v_pk_fma_f32 v[138:139], v[118:119], v[150:151], v[138:139]
	v_max_f32_e32 v136, v136, v136
	v_pk_fma_f32 v[138:139], v[120:121], v[154:155], v[138:139]
	v_pk_fma_f32 v[142:143], v[124:125], v[164:165], v[142:143]
	v_pk_fma_f32 v[138:139], v[122:123], v[158:159], v[138:139]
	v_max_f32_e32 v136, 0, v136
	v_pk_fma_f32 v[138:139], v[124:125], v[162:163], v[138:139]
	v_max_f32_e32 v137, 0, v137
	v_pk_fma_f32 v[138:139], v[126:127], v[166:167], v[138:139]
	v_pk_fma_f32 v[142:143], v[126:127], v[168:169], v[142:143]
	v_pk_fma_f32 v[136:137], v[128:129], v[136:137], v[138:139]
	v_pk_fma_f32 v[138:139], v[128:129], v[140:141], v[142:143]
	v_cvt_pk_f16_f32 v136, v136, v137
	v_cvt_pk_f16_f32 v137, v138, v139
	v_and_b32_e32 v138, 0xffff0000, v137
	v_lshlrev_b32_e32 v139, 16, v137
	v_or_b32_sdwa v137, v138, v136 dst_sel:DWORD dst_unused:UNUSED_PAD src0_sel:DWORD src1_sel:WORD_1
	v_or_b32_sdwa v136, v139, v136 dst_sel:DWORD dst_unused:UNUSED_PAD src0_sel:DWORD src1_sel:WORD_0
	ds_write_b64 v0, v[136:137] offset:1024
	s_andn2_b64 vcc, exec, s[4:5]
	s_cbranch_vccnz .LBB0_595
.LBB0_615:
	s_cmp_ge_i32 s2, s3
	s_cbranch_scc1 .LBB0_594
	global_load_dwordx4 v[98:101], v[130:131], off offset:-64
	global_load_dwordx4 v[102:105], v[130:131], off
	s_waitcnt vmcnt(10)
	s_branch .Ls1body_594
